# GEMM phase prologue: second batch of tile loads issued before the first wait; plus aligned loops, HID sc1, phase-B rewrites
# speedup vs baseline: 1.0036x; 1.0036x over previous
.LBB0_432:
	v_readlane_b32 s6, v244, 1
	s_add_u32 s6, s92, s6
	v_readlane_b32 s7, v245, 62
	s_addc_u32 s7, s93, s7
	s_add_u32 s6, s6, 0x1d900000
	v_bfe_u32 v12, v10, 4, 2
	s_addc_u32 s7, s7, 0
	v_and_b32_e32 v11, 15, v10
	v_lshlrev_b32_e32 v13, 4, v12
	v_lshlrev_b32_e32 v10, 2, v10
	s_lshl_b32 s20, s20, 5
	v_lshl_or_b32 v190, s21, 6, v11
	v_lshl_or_b32 v11, v11, 6, v13
	s_lshl_b32 s21, s21, 13
	v_and_b32_e32 v10, 32, v10
	s_and_b32 s20, s20, 0x60
	v_bitop3_b32 v13, v11, s21, v10 bitop3:0xde
	s_lshl_b32 s21, s20, 7
	v_bitop3_b32 v191, v11, s21, v10 bitop3:0xde
	v_lshl_add_u64 v[10:11], v[2:3], 0, s[34:35]
	s_add_i32 m0, s47, 0x18000
	s_nop 0
	global_load_lds_dwordx4 v[10:11], off
	v_lshl_add_u64 v[10:11], v[2:3], 0, s[12:13]
	s_add_i32 m0, s47, 0x1a000
	s_add_i32 s77, s47, 0x8000
	global_load_lds_dwordx4 v[10:11], off
	v_lshl_add_u64 v[10:11], v[4:5], 0, s[34:35]
	s_mov_b32 m0, s77
	s_add_i32 s78, s47, 0xa000
	global_load_lds_dwordx4 v[10:11], off
	v_lshl_add_u64 v[4:5], v[4:5], 0, s[12:13]
	s_mov_b32 m0, s78
	s_movk_i32 s12, 0xb00
	global_load_lds_dwordx4 v[4:5], off
	v_lshl_add_u64 v[4:5], v[2:3], 0, s[22:23]
	s_add_i32 m0, s47, 0x1c000
	v_lshl_add_u64 v[2:3], v[2:3], 0, s[0:1]
	global_load_lds_dwordx4 v[4:5], off
	s_add_i32 m0, s47, 0x1e000
	v_lshl_or_b32 v192, v12, 3, s20
	global_load_lds_dwordx4 v[2:3], off
	v_lshrrev_b32_e32 v3, 1, v7
	v_mul_lo_u32 v2, v6, s12
	s_mov_b32 s20, 0xb000
	s_waitcnt vmcnt(8)
	s_barrier
	s_waitcnt vmcnt(6)
	v_mad_u64_u32 v[2:3], s[20:21], v3, s20, v[2:3]
	s_cmpk_lt_u32 s40, 0x100
	v_or_b32_e32 v2, v2, v8
	v_readlane_b32 s12, v245, 17
	s_cselect_b64 s[40:41], -1, 0
	s_mov_b32 s79, 0
	v_cmp_eq_u32_e64 s[52:53], 0, v12
	v_add_lshl_u32 v156, v2, v9, 1
	v_mov_b32_e32 v157, v1
	v_add_u32_e32 v193, 0, v13
	v_readlane_b32 s90, v246, 56
	s_mov_b32 s91, s12
	s_barrier
	v_readlane_b32 s13, v245, 18
	s_branch .LBB0_435

.LBB0_482:
	v_and_b32_e32 v10, 15, v9
	v_lshrrev_b32_e32 v9, 1, v9
	v_and_b32_e32 v9, 24, v9
	v_lshlrev_b32_e32 v11, 1, v9
	v_lshlrev_b32_e32 v12, 2, v10
	s_lshl_b32 s20, s20, 5
	v_lshl_or_b32 v138, s51, 6, v10
	v_lshl_or_b32 v11, v10, 6, v11
	s_lshl_b32 s21, s51, 13
	v_and_b32_e32 v10, 32, v12
	s_and_b32 s20, s20, 0x60
	v_bitop3_b32 v13, v11, s21, v10 bitop3:0xde
	s_lshl_b32 s21, s20, 7
	s_add_u32 s40, s92, 0x12800000
	v_bitop3_b32 v139, v11, s21, v10 bitop3:0xde
	s_addc_u32 s41, s93, 0
	v_lshl_add_u64 v[10:11], v[2:3], 0, s[34:35]
	s_add_i32 m0, s43, 0x18000
	s_nop 0
	global_load_lds_dwordx4 v[10:11], off
	v_lshl_add_u64 v[10:11], v[2:3], 0, s[38:39]
	s_add_i32 m0, s43, 0x1a000
	s_add_i32 s79, s43, 0x8000
	global_load_lds_dwordx4 v[10:11], off
	v_lshl_add_u64 v[10:11], v[4:5], 0, s[34:35]
	s_mov_b32 m0, s79
	s_add_i32 s88, s43, 0xa000
	global_load_lds_dwordx4 v[10:11], off
	v_lshl_add_u64 v[4:5], v[4:5], 0, s[38:39]
	s_mov_b32 m0, s88
	v_readlane_b32 s12, v245, 7
	global_load_lds_dwordx4 v[4:5], off
	v_lshl_add_u64 v[4:5], v[2:3], 0, s[44:45]
	s_add_i32 m0, s43, 0x1c000
	v_lshl_add_u64 v[2:3], v[2:3], 0, s[10:11]
	global_load_lds_dwordx4 v[4:5], off
	s_add_i32 m0, s43, 0x1e000
	s_cmpk_lt_u32 s48, 0x100
	global_load_lds_dwordx4 v[2:3], off
	v_lshlrev_b32_e32 v2, 14, v7
	v_and_b32_e32 v2, 0xffff8000, v2
	s_waitcnt vmcnt(8)
	s_barrier
	s_waitcnt vmcnt(6)
	s_cselect_b64 s[48:49], -1, 0
	s_lshl_b32 s21, s51, 8
	v_lshl_add_u32 v2, v6, 11, v2
	v_and_b32_e32 v3, 1, v7
	s_add_i32 s21, s50, s21
	v_lshl_or_b32 v2, v3, 6, v2
	v_add_u32_e32 v140, s21, v12
	v_or_b32_e32 v141, s20, v9
	v_lshl_add_u32 v132, v8, 1, v2
	v_mov_b32_e32 v133, v1
	s_mov_b32 s85, 0
	v_add_u32_e32 v142, 0, v13
	v_readlane_b32 s90, v246, 57
	s_mov_b32 s84, s12
	s_barrier
	v_readlane_b32 s13, v245, 8
	s_branch .LBB0_485

.LBB0_552:
	v_bfe_u32 v11, v8, 4, 2
	s_add_u32 s6, s50, 0xc0000
	v_and_b32_e32 v10, 15, v8
	v_lshlrev_b32_e32 v9, 4, v11
	v_lshlrev_b32_e32 v8, 2, v8
	s_addc_u32 s7, s51, 0
	v_lshl_or_b32 v9, v10, 6, v9
	s_lshl_b32 s21, s41, 13
	v_and_b32_e32 v8, 32, v8
	s_lshl_b32 s20, s20, 5
	v_bitop3_b32 v12, v9, s21, v8 bitop3:0xde
	s_and_b32 s21, s20, 0x60
	s_lshl_b32 s20, s21, 7
	v_bitop3_b32 v215, v9, s20, v8 bitop3:0xde
	v_lshl_add_u64 v[8:9], v[2:3], 0, s[34:35]
	s_add_i32 m0, s47, 0x18000
	s_nop 0
	global_load_lds_dwordx4 v[8:9], off
	v_lshl_add_u64 v[8:9], v[2:3], 0, s[38:39]
	s_add_i32 m0, s47, 0x1a000
	s_add_i32 s90, s47, 0x8000
	global_load_lds_dwordx4 v[8:9], off
	v_lshl_add_u64 v[8:9], v[4:5], 0, s[34:35]
	s_mov_b32 m0, s90
	s_add_i32 s91, s47, 0xa000
	global_load_lds_dwordx4 v[8:9], off
	v_lshl_add_u64 v[4:5], v[4:5], 0, s[38:39]
	s_mov_b32 m0, s91
	s_lshl_b32 s22, s41, 9
	global_load_lds_dwordx4 v[4:5], off
	v_lshl_add_u64 v[4:5], v[2:3], 0, s[44:45]
	s_add_i32 m0, s47, 0x1c000
	v_lshl_add_u64 v[2:3], v[2:3], 0, s[10:11]
	global_load_lds_dwordx4 v[4:5], off
	s_add_i32 m0, s47, 0x1e000
	s_cmpk_lt_u32 s40, 0x100
	global_load_lds_dwordx4 v[2:3], off
	v_lshlrev_b32_e32 v2, 14, v6
	v_and_b32_e32 v2, 0xffff8000, v2
	v_lshl_or_b32 v214, s41, 6, v10
	s_waitcnt vmcnt(8)
	s_barrier
	s_waitcnt vmcnt(6)
	s_cselect_b64 s[40:41], -1, 0
	s_add_i32 s22, s22, 0
	v_lshl_add_u32 v0, v0, 11, v2
	v_and_b32_e32 v2, 1, v6
	s_add_i32 s22, s22, 0x20000
	v_lshl_or_b32 v0, v2, 6, v0
	v_readlane_b32 s12, v245, 17
	s_mov_b32 s20, 0
	v_cmp_eq_u32_e64 s[52:53], 0, v11
	v_lshl_add_u32 v216, v10, 3, s22
	v_lshl_or_b32 v217, v11, 3, s21
	v_lshl_add_u32 v186, v7, 1, v0
	v_mov_b32_e32 v187, v1
	v_add_u32_e32 v218, 0, v12
	v_readlane_b32 s84, v246, 56
	s_mov_b32 s85, s12
	s_barrier
	v_readlane_b32 s13, v245, 18
	s_branch .LBB0_555

.LBB0_594:
	s_add_u32 s60, s92, 0x19800000
	s_addc_u32 s61, s93, 0
	v_readlane_b32 s12, v244, 1
	s_add_u32 s21, s92, s12
	v_readlane_b32 s12, v245, 62
	s_addc_u32 s22, s93, s12
	s_add_u32 s62, s21, 0x1d840000
	v_bfe_u32 v12, v9, 4, 2
	s_addc_u32 s63, s22, 0
	v_and_b32_e32 v10, 15, v9
	v_lshlrev_b32_e32 v11, 4, v12
	v_lshlrev_b32_e32 v9, 2, v9
	s_lshl_b32 s15, s15, 5
	v_lshl_or_b32 v138, s20, 6, v10
	v_lshl_or_b32 v10, v10, 6, v11
	s_lshl_b32 s20, s20, 13
	v_and_b32_e32 v9, 32, v9
	s_and_b32 s15, s15, 0x60
	v_bitop3_b32 v13, v10, s20, v9 bitop3:0xde
	s_lshl_b32 s20, s15, 7
	v_bitop3_b32 v139, v10, s20, v9 bitop3:0xde
	v_lshl_add_u64 v[10:11], v[2:3], 0, s[34:35]
	s_add_i32 m0, s89, 0x18000
	s_nop 0
	global_load_lds_dwordx4 v[10:11], off
	v_lshl_add_u64 v[10:11], v[2:3], 0, s[80:81]
	s_add_i32 m0, s89, 0x1a000
	s_add_i32 s97, s89, 0x8000
	global_load_lds_dwordx4 v[10:11], off
	v_lshl_add_u64 v[10:11], v[4:5], 0, s[34:35]
	s_mov_b32 m0, s97
	s_add_i32 s58, s89, 0xa000
	global_load_lds_dwordx4 v[10:11], off
	v_lshl_add_u64 v[4:5], v[4:5], 0, s[80:81]
	s_mov_b32 m0, s58
	v_readlane_b32 s12, v245, 21
	global_load_lds_dwordx4 v[4:5], off
	v_lshl_add_u64 v[4:5], v[2:3], 0, s[38:39]
	s_add_i32 m0, s89, 0x1c000
	v_lshl_add_u64 v[2:3], v[2:3], 0, s[86:87]
	global_load_lds_dwordx4 v[4:5], off
	s_add_i32 m0, s89, 0x1e000
	s_cmpk_lt_u32 s14, 0x100
	global_load_lds_dwordx4 v[2:3], off
	v_lshlrev_b32_e32 v2, 13, v7
	v_and_b32_e32 v2, 0xffffc000, v2
	s_waitcnt vmcnt(8)
	s_barrier
	s_waitcnt vmcnt(6)
	v_lshl_add_u32 v2, v6, 10, v2
	v_and_b32_e32 v3, 1, v7
	v_lshl_or_b32 v2, v3, 6, v2
	s_cselect_b64 s[52:53], -1, 0
	s_mov_b32 s59, 0
	v_cmp_eq_u32_e64 s[54:55], 0, v12
	v_lshl_or_b32 v140, v12, 3, s15
	v_lshl_add_u32 v132, v8, 1, v2
	v_mov_b32_e32 v133, v1
	v_add_u32_e32 v141, 0, v13
	v_readlane_b32 s14, v246, 60
	s_mov_b32 s15, s12
	s_barrier
	v_readlane_b32 s13, v245, 22
	s_branch .LBB0_597

.LBB0_632:
	v_lshrrev_b32_e32 v8, 1, v6
	v_and_b32_e32 v8, 24, v8
	s_add_u32 s6, s92, 0xe800000
	v_and_b32_e32 v7, 15, v6
	v_lshlrev_b32_e32 v9, 1, v8
	v_lshlrev_b32_e32 v6, 2, v6
	s_addc_u32 s7, s93, 0
	v_lshl_or_b32 v132, s14, 6, v7
	v_lshl_or_b32 v7, v7, 6, v9
	s_lshl_b32 s14, s14, 13
	v_and_b32_e32 v6, 32, v6
	s_lshl_b32 s0, s0, 5
	v_bitop3_b32 v9, v7, s14, v6 bitop3:0xde
	s_and_b32 s14, s0, 0x60
	s_lshl_b32 s0, s14, 7
	v_bitop3_b32 v133, v7, s0, v6 bitop3:0xde
	v_lshl_add_u64 v[6:7], v[2:3], 0, s[34:35]
	s_add_i32 m0, s47, 0x18000
	s_nop 0
	global_load_lds_dwordx4 v[6:7], off
	v_lshl_add_u64 v[6:7], v[2:3], 0, s[70:71]
	s_add_i32 m0, s47, 0x1a000
	s_add_i32 s97, s47, 0x8000
	global_load_lds_dwordx4 v[6:7], off
	v_lshl_add_u64 v[6:7], v[4:5], 0, s[34:35]
	s_mov_b32 m0, s97
	s_add_i32 s0, s47, 0xa000
	global_load_lds_dwordx4 v[6:7], off
	v_lshl_add_u64 v[4:5], v[4:5], 0, s[70:71]
	s_mov_b32 m0, s0
	v_or_b32_e32 v134, s14, v8
	global_load_lds_dwordx4 v[4:5], off
	v_lshl_add_u64 v[4:5], v[2:3], 0, s[80:81]
	s_add_i32 m0, s47, 0x1c000
	v_lshl_add_u64 v[2:3], v[2:3], 0, s[30:31]
	global_load_lds_dwordx4 v[4:5], off
	s_add_i32 m0, s47, 0x1e000
	s_cmpk_lt_u32 s1, 0x100
	global_load_lds_dwordx4 v[2:3], off
	s_cselect_b64 s[12:13], -1, 0
	s_waitcnt vmcnt(8)
	s_barrier
	s_waitcnt vmcnt(6)
	v_writelane_b32 v244, s12, 8
	s_mov_b32 s1, 0
	v_add_u32_e32 v135, 0, v9
	v_writelane_b32 v244, s13, 9
	v_readlane_b32 s12, v245, 17
	v_readlane_b32 s14, v246, 56
	s_mov_b32 s15, s12
	s_barrier
	v_readlane_b32 s13, v245, 18
	s_branch .LBB0_635

.LBB0_768:
	v_and_b32_e32 v10, 15, v9
	v_bfe_u32 v9, v9, 4, 2
	v_lshlrev_b32_e32 v11, 4, v9
	v_lshlrev_b32_e32 v12, 2, v10
	s_lshl_b32 s20, s20, 5
	v_lshl_or_b32 v192, s57, 6, v10
	v_lshl_or_b32 v11, v10, 6, v11
	s_lshl_b32 s21, s57, 13
	v_and_b32_e32 v10, 32, v12
	s_and_b32 s20, s20, 0x60
	v_bitop3_b32 v13, v11, s21, v10 bitop3:0xde
	s_lshl_b32 s21, s20, 7
	s_add_u32 s48, s92, 0xe800000
	v_bitop3_b32 v193, v11, s21, v10 bitop3:0xde
	s_addc_u32 s49, s93, 0
	v_lshl_add_u64 v[10:11], v[2:3], 0, s[34:35]
	s_add_i32 m0, s43, 0x18000
	s_nop 0
	global_load_lds_dwordx4 v[10:11], off
	v_lshl_add_u64 v[10:11], v[2:3], 0, s[38:39]
	s_add_i32 m0, s43, 0x1a000
	s_add_i32 s89, s43, 0x8000
	global_load_lds_dwordx4 v[10:11], off
	v_lshl_add_u64 v[10:11], v[4:5], 0, s[34:35]
	s_mov_b32 m0, s89
	s_add_i32 s90, s43, 0xa000
	global_load_lds_dwordx4 v[10:11], off
	v_lshl_add_u64 v[4:5], v[4:5], 0, s[38:39]
	s_mov_b32 m0, s90
	v_readlane_b32 s12, v245, 17
	global_load_lds_dwordx4 v[4:5], off
	v_lshl_add_u64 v[4:5], v[2:3], 0, s[44:45]
	s_add_i32 m0, s43, 0x1c000
	v_lshl_add_u64 v[2:3], v[2:3], 0, s[10:11]
	global_load_lds_dwordx4 v[4:5], off
	s_add_i32 m0, s43, 0x1e000
	s_cmpk_lt_u32 s50, 0x100
	global_load_lds_dwordx4 v[2:3], off
	v_lshlrev_b32_e32 v2, 14, v7
	v_and_b32_e32 v2, 0xffff8000, v2
	s_waitcnt vmcnt(8)
	s_barrier
	s_waitcnt vmcnt(6)
	s_cselect_b64 s[50:51], -1, 0
	s_lshl_b32 s21, s57, 8
	v_lshl_add_u32 v2, v6, 11, v2
	v_and_b32_e32 v3, 1, v7
	s_add_i32 s56, s56, s21
	v_lshl_or_b32 v2, v3, 6, v2
	s_mov_b32 s96, 0
	v_cmp_eq_u32_e64 s[54:55], 0, v9
	v_add_u32_e32 v194, s56, v12
	v_lshl_or_b32 v195, v9, 3, s20
	v_lshl_add_u32 v182, v8, 1, v2
	v_mov_b32_e32 v183, v1
	v_add_u32_e32 v196, 0, v13
	v_readlane_b32 s97, v246, 56
	s_mov_b32 s84, s12
	s_barrier
	v_readlane_b32 s13, v245, 18
	s_branch .LBB0_771

.LBB0_844:
	v_lshrrev_b32_e32 v10, 1, v8
	v_and_b32_e32 v9, 15, v8
	v_and_b32_e32 v11, 24, v10
	v_lshlrev_b32_e32 v8, 1, v11
	v_lshlrev_b32_e32 v12, 2, v9
	s_lshl_b32 s20, s20, 5
	v_lshl_or_b32 v135, s55, 6, v9
	v_lshl_or_b32 v8, v9, 6, v8
	s_lshl_b32 s21, s55, 13
	v_and_b32_e32 v9, 32, v12
	s_and_b32 s20, s20, 0x60
	v_bitop3_b32 v13, v8, s21, v9 bitop3:0xde
	s_lshl_b32 s21, s20, 7
	s_add_u32 s40, s92, 0x12800000
	s_addc_u32 s41, s93, 0
	s_add_u32 s48, s92, 0x14800000
	s_addc_u32 s49, s93, 0
	s_add_u32 s50, s92, 0x16800000
	s_addc_u32 s51, s93, 0
	s_add_u32 s60, s92, 0x17000000
	v_bitop3_b32 v145, v8, s21, v9 bitop3:0xde
	s_addc_u32 s61, s93, 0
	v_lshl_add_u64 v[8:9], v[2:3], 0, s[34:35]
	s_add_i32 m0, s15, 0x18000
	s_nop 0
	global_load_lds_dwordx4 v[8:9], off
	v_lshl_add_u64 v[8:9], v[2:3], 0, s[38:39]
	s_add_i32 m0, s15, 0x1a000
	s_add_i32 s47, s15, 0x8000
	global_load_lds_dwordx4 v[8:9], off
	v_lshl_add_u64 v[8:9], v[4:5], 0, s[34:35]
	s_mov_b32 m0, s47
	s_add_i32 s96, s15, 0xa000
	global_load_lds_dwordx4 v[8:9], off
	v_lshl_add_u64 v[4:5], v[4:5], 0, s[38:39]
	s_mov_b32 m0, s96
	v_or_b32_e32 v155, s20, v11
	global_load_lds_dwordx4 v[4:5], off
	v_lshl_add_u64 v[4:5], v[2:3], 0, s[44:45]
	s_add_i32 m0, s15, 0x1c000
	v_lshl_add_u64 v[2:3], v[2:3], 0, s[10:11]
	global_load_lds_dwordx4 v[4:5], off
	s_add_i32 m0, s15, 0x1e000
	s_cmpk_lt_u32 s62, 0x100
	global_load_lds_dwordx4 v[2:3], off
	v_lshlrev_b32_e32 v2, 14, v6
	v_and_b32_e32 v2, 0xffff8000, v2
	s_waitcnt vmcnt(8)
	s_barrier
	s_waitcnt vmcnt(6)
	s_cselect_b64 s[62:63], -1, 0
	s_lshl_b32 s20, s55, 8
	v_lshl_add_u32 v0, v0, 11, v2
	v_and_b32_e32 v2, 1, v6
	s_add_i32 s20, s54, s20
	v_lshl_or_b32 v0, v2, 6, v0
	v_readlane_b32 s12, v245, 25
	v_and_b32_e32 v134, 8, v10
	v_add_u32_e32 v156, s20, v12
	v_lshl_add_u32 v136, v7, 1, v0
	v_mov_b32_e32 v137, v1
	s_mov_b32 s85, 0
	v_add_u32_e32 v157, 0, v13
	v_readlane_b32 s90, v246, 61
	s_mov_b32 s84, s12
	s_barrier
	v_readlane_b32 s13, v245, 26
	s_branch .LBB0_847

.LBB0_1046:
	v_lshrrev_b32_e32 v8, 1, v6
	v_and_b32_e32 v8, 24, v8
	s_add_u32 s4, s92, 0xe800000
	v_and_b32_e32 v7, 15, v6
	v_lshlrev_b32_e32 v9, 1, v8
	v_lshlrev_b32_e32 v6, 2, v6
	s_addc_u32 s5, s93, 0
	v_lshl_or_b32 v132, s20, 6, v7
	v_lshl_or_b32 v7, v7, 6, v9
	s_lshl_b32 s20, s20, 13
	v_and_b32_e32 v6, 32, v6
	s_lshl_b32 s7, s7, 5
	v_bitop3_b32 v9, v7, s20, v6 bitop3:0xde
	s_and_b32 s20, s7, 0x60
	s_lshl_b32 s7, s20, 7
	v_bitop3_b32 v133, v7, s7, v6 bitop3:0xde
	v_lshl_add_u64 v[6:7], v[2:3], 0, s[34:35]
	s_add_i32 m0, s22, 0x18000
	s_nop 0
	global_load_lds_dwordx4 v[6:7], off
	v_lshl_add_u64 v[6:7], v[2:3], 0, s[70:71]
	s_add_i32 m0, s22, 0x1a000
	s_add_i32 s91, s22, 0x8000
	global_load_lds_dwordx4 v[6:7], off
	v_lshl_add_u64 v[6:7], v[4:5], 0, s[34:35]
	s_mov_b32 m0, s91
	s_add_i32 s92, s22, 0xa000
	global_load_lds_dwordx4 v[6:7], off
	v_lshl_add_u64 v[4:5], v[4:5], 0, s[70:71]
	s_mov_b32 m0, s92
	v_readlane_b32 s12, v245, 55
	global_load_lds_dwordx4 v[4:5], off
	v_lshl_add_u64 v[4:5], v[2:3], 0, s[80:81]
	s_add_i32 m0, s22, 0x1c000
	v_lshl_add_u64 v[2:3], v[2:3], 0, s[30:31]
	global_load_lds_dwordx4 v[4:5], off
	s_add_i32 m0, s22, 0x1e000
	v_readlane_b32 s13, v245, 56
	global_load_lds_dwordx4 v[2:3], off
	s_mov_b32 s12, 0
	s_waitcnt vmcnt(8)
	s_barrier
	s_waitcnt vmcnt(6)
	v_writelane_b32 v245, s12, 55
	s_cmpk_lt_u32 s6, 0x100
	s_cselect_b64 s[6:7], -1, 0
	v_writelane_b32 v245, s13, 56
	v_or_b32_e32 v134, s20, v8
	v_add_u32_e32 v135, 0, v9
	v_readlane_b32 s84, v245, 1
	v_readlane_b32 s85, v246, 63
	s_barrier
	s_branch .LBB0_1049
